# layer-1 out-projection epilogue fused with the final RMSNorm: residual sum kept in registers across the last barrier, row sums of squares by f32 atomics, no XB round trip; layer-0 out epilogue softwar
# baseline (speedup 1.0000x reference)
.Lmg_fin:
	v_readlane_b32 s2, v251, 0
	s_add_u32 s14, s24, 0x28064000
	s_addc_u32 s15, s25, 0
	s_lshl_b32 s2, s2, 7
	s_lshr_b32 s3, s21, 6
	s_add_i32 s2, s2, s3
	v_lshl_add_u32 v161, v217, 2, s2
	v_mov_b32_e32 v162, 0
	v_cmp_gt_u32_e32 vcc, 4, v217
	s_and_saveexec_b64 s[42:43], vcc
	global_store_dword v161, v162, s[14:15]
	s_mov_b64 exec, s[42:43]
	v_add_u32_e32 v142, 0x5a00, v142
	global_load_dwordx4 v[164:167], v142, s[34:35]
	global_load_dwordx4 v[168:171], v142, s[34:35] offset:256
	v_add_u32_e32 v142, 0x6a000, v142
	global_load_dwordx4 v[172:175], v142, s[34:35]
	global_load_dwordx4 v[176:179], v142, s[34:35] offset:256
	v_add_u32_e32 v142, 0x6a000, v142
	global_load_dwordx4 v[180:183], v142, s[34:35]
	global_load_dwordx4 v[184:187], v142, s[34:35] offset:256
	v_add_u32_e32 v142, 0x6a000, v142
	global_load_dwordx4 v[188:191], v142, s[34:35]
	global_load_dwordx4 v[192:195], v142, s[34:35] offset:256
	v_add_u32_e32 v142, 0x212000, v142
	global_load_dwordx4 v[196:199], v142, s[34:35]
	global_load_dwordx4 v[224:227], v142, s[34:35] offset:256
	v_add_u32_e32 v142, 0x6a000, v142
	s_waitcnt vmcnt(9)
	v_lshlrev_b32_e32 v244, 16, v164
	v_and_b32_e32 v245, 0xffff0000, v164
	v_lshlrev_b32_e32 v246, 16, v165
	v_and_b32_e32 v247, 0xffff0000, v165
	v_lshlrev_b32_e32 v248, 16, v166
	v_and_b32_e32 v249, 0xffff0000, v166
	v_lshlrev_b32_e32 v140, 16, v167
	v_and_b32_e32 v141, 0xffff0000, v167
	v_mul_f32_e32 v126, v126, v244
	v_mul_f32_e32 v127, v127, v245
	v_mul_f32_e32 v128, v128, v246
	v_mul_f32_e32 v129, v129, v247
	v_mul_f32_e32 v122, v122, v248
	v_mul_f32_e32 v123, v123, v249
	v_mul_f32_e32 v124, v124, v140
	v_mul_f32_e32 v125, v125, v141
	v_cvt_pk_bf16_f32 v164, v126, v127
	v_cvt_pk_bf16_f32 v165, v128, v129
	v_cvt_pk_bf16_f32 v166, v122, v123
	v_cvt_pk_bf16_f32 v167, v124, v125
	global_store_dwordx4 v143, v[164:167], s[16:17]
	s_nop 0
	global_load_dwordx4 v[164:167], v142, s[34:35]
	s_waitcnt vmcnt(10)
	v_lshlrev_b32_e32 v244, 16, v168
	v_and_b32_e32 v245, 0xffff0000, v168
	v_lshlrev_b32_e32 v246, 16, v169
	v_and_b32_e32 v247, 0xffff0000, v169
	v_lshlrev_b32_e32 v248, 16, v170
	v_and_b32_e32 v249, 0xffff0000, v170
	v_lshlrev_b32_e32 v140, 16, v171
	v_and_b32_e32 v141, 0xffff0000, v171
	v_mul_f32_e32 v94, v94, v244
	v_mul_f32_e32 v95, v95, v245
	v_mul_f32_e32 v96, v96, v246
	v_mul_f32_e32 v97, v97, v247
	v_mul_f32_e32 v90, v90, v248
	v_mul_f32_e32 v91, v91, v249
	v_mul_f32_e32 v92, v92, v140
	v_mul_f32_e32 v93, v93, v141
	v_cvt_pk_bf16_f32 v168, v94, v95
	v_cvt_pk_bf16_f32 v169, v96, v97
	v_cvt_pk_bf16_f32 v170, v90, v91
	v_cvt_pk_bf16_f32 v171, v92, v93
	global_store_dwordx4 v143, v[168:171], s[16:17] offset:256
	v_add_u32_e32 v143, 0x10000, v143
	global_load_dwordx4 v[168:171], v142, s[34:35] offset:256
	v_add_u32_e32 v142, 0x6a000, v142
	s_waitcnt vmcnt(11)
	v_lshlrev_b32_e32 v244, 16, v172
	v_and_b32_e32 v245, 0xffff0000, v172
	v_lshlrev_b32_e32 v246, 16, v173
	v_and_b32_e32 v247, 0xffff0000, v173
	v_lshlrev_b32_e32 v248, 16, v174
	v_and_b32_e32 v249, 0xffff0000, v174
	v_lshlrev_b32_e32 v140, 16, v175
	v_and_b32_e32 v141, 0xffff0000, v175
	v_mul_f32_e32 v118, v118, v244
	v_mul_f32_e32 v119, v119, v245
	v_mul_f32_e32 v120, v120, v246
	v_mul_f32_e32 v121, v121, v247
	v_mul_f32_e32 v114, v114, v248
	v_mul_f32_e32 v115, v115, v249
	v_mul_f32_e32 v116, v116, v140
	v_mul_f32_e32 v117, v117, v141
	v_cvt_pk_bf16_f32 v172, v118, v119
	v_cvt_pk_bf16_f32 v173, v120, v121
	v_cvt_pk_bf16_f32 v174, v114, v115
	v_cvt_pk_bf16_f32 v175, v116, v117
	global_store_dwordx4 v143, v[172:175], s[16:17]
	s_nop 0
	global_load_dwordx4 v[172:175], v142, s[34:35]
	s_waitcnt vmcnt(12)
	v_lshlrev_b32_e32 v244, 16, v176
	v_and_b32_e32 v245, 0xffff0000, v176
	v_lshlrev_b32_e32 v246, 16, v177
	v_and_b32_e32 v247, 0xffff0000, v177
	v_lshlrev_b32_e32 v248, 16, v178
	v_and_b32_e32 v249, 0xffff0000, v178
	v_lshlrev_b32_e32 v140, 16, v179
	v_and_b32_e32 v141, 0xffff0000, v179
	v_mul_f32_e32 v86, v86, v244
	v_mul_f32_e32 v87, v87, v245
	v_mul_f32_e32 v88, v88, v246
	v_mul_f32_e32 v89, v89, v247
	v_mul_f32_e32 v82, v82, v248
	v_mul_f32_e32 v83, v83, v249
	v_mul_f32_e32 v84, v84, v140
	v_mul_f32_e32 v85, v85, v141
	v_cvt_pk_bf16_f32 v176, v86, v87
	v_cvt_pk_bf16_f32 v177, v88, v89
	v_cvt_pk_bf16_f32 v178, v82, v83
	v_cvt_pk_bf16_f32 v179, v84, v85
	global_store_dwordx4 v143, v[176:179], s[16:17] offset:256
	v_add_u32_e32 v143, 0x10000, v143
	global_load_dwordx4 v[176:179], v142, s[34:35] offset:256
	v_add_u32_e32 v142, 0x6a000, v142
	s_waitcnt vmcnt(13)
	v_lshlrev_b32_e32 v244, 16, v180
	v_and_b32_e32 v245, 0xffff0000, v180
	v_lshlrev_b32_e32 v246, 16, v181
	v_and_b32_e32 v247, 0xffff0000, v181
	v_lshlrev_b32_e32 v248, 16, v182
	v_and_b32_e32 v249, 0xffff0000, v182
	v_lshlrev_b32_e32 v140, 16, v183
	v_and_b32_e32 v141, 0xffff0000, v183
	v_mul_f32_e32 v110, v110, v244
	v_mul_f32_e32 v111, v111, v245
	v_mul_f32_e32 v112, v112, v246
	v_mul_f32_e32 v113, v113, v247
	v_mul_f32_e32 v106, v106, v248
	v_mul_f32_e32 v107, v107, v249
	v_mul_f32_e32 v108, v108, v140
	v_mul_f32_e32 v109, v109, v141
	v_cvt_pk_bf16_f32 v180, v110, v111
	v_cvt_pk_bf16_f32 v181, v112, v113
	v_cvt_pk_bf16_f32 v182, v106, v107
	v_cvt_pk_bf16_f32 v183, v108, v109
	global_store_dwordx4 v143, v[180:183], s[16:17]
	s_nop 0
	global_load_dwordx4 v[180:183], v142, s[34:35]
	s_waitcnt vmcnt(14)
	v_lshlrev_b32_e32 v244, 16, v184
	v_and_b32_e32 v245, 0xffff0000, v184
	v_lshlrev_b32_e32 v246, 16, v185
	v_and_b32_e32 v247, 0xffff0000, v185
	v_lshlrev_b32_e32 v248, 16, v186
	v_and_b32_e32 v249, 0xffff0000, v186
	v_lshlrev_b32_e32 v140, 16, v187
	v_and_b32_e32 v141, 0xffff0000, v187
	v_mul_f32_e32 v78, v78, v244
	v_mul_f32_e32 v79, v79, v245
	v_mul_f32_e32 v80, v80, v246
	v_mul_f32_e32 v81, v81, v247
	v_mul_f32_e32 v74, v74, v248
	v_mul_f32_e32 v75, v75, v249
	v_mul_f32_e32 v76, v76, v140
	v_mul_f32_e32 v77, v77, v141
	v_cvt_pk_bf16_f32 v184, v78, v79
	v_cvt_pk_bf16_f32 v185, v80, v81
	v_cvt_pk_bf16_f32 v186, v74, v75
	v_cvt_pk_bf16_f32 v187, v76, v77
	global_store_dwordx4 v143, v[184:187], s[16:17] offset:256
	v_add_u32_e32 v143, 0x10000, v143
	global_load_dwordx4 v[184:187], v142, s[34:35] offset:256
	s_waitcnt vmcnt(15)
	v_lshlrev_b32_e32 v244, 16, v188
	v_and_b32_e32 v245, 0xffff0000, v188
	v_lshlrev_b32_e32 v246, 16, v189
	v_and_b32_e32 v247, 0xffff0000, v189
	v_lshlrev_b32_e32 v248, 16, v190
	v_and_b32_e32 v249, 0xffff0000, v190
	v_lshlrev_b32_e32 v140, 16, v191
	v_and_b32_e32 v141, 0xffff0000, v191
	v_mul_f32_e32 v102, v102, v244
	v_mul_f32_e32 v103, v103, v245
	v_mul_f32_e32 v104, v104, v246
	v_mul_f32_e32 v105, v105, v247
	v_mul_f32_e32 v98, v98, v248
	v_mul_f32_e32 v99, v99, v249
	v_mul_f32_e32 v100, v100, v140
	v_mul_f32_e32 v101, v101, v141
	v_cvt_pk_bf16_f32 v188, v102, v103
	v_cvt_pk_bf16_f32 v189, v104, v105
	v_cvt_pk_bf16_f32 v190, v98, v99
	v_cvt_pk_bf16_f32 v191, v100, v101
	global_store_dwordx4 v143, v[188:191], s[16:17]
	s_nop 0
	s_waitcnt vmcnt(15)
	v_lshlrev_b32_e32 v244, 16, v192
	v_and_b32_e32 v245, 0xffff0000, v192
	v_lshlrev_b32_e32 v246, 16, v193
	v_and_b32_e32 v247, 0xffff0000, v193
	v_lshlrev_b32_e32 v248, 16, v194
	v_and_b32_e32 v249, 0xffff0000, v194
	v_lshlrev_b32_e32 v140, 16, v195
	v_and_b32_e32 v141, 0xffff0000, v195
	v_mul_f32_e32 v70, v70, v244
	v_mul_f32_e32 v71, v71, v245
	v_mul_f32_e32 v72, v72, v246
	v_mul_f32_e32 v73, v73, v247
	v_mul_f32_e32 v66, v66, v248
	v_mul_f32_e32 v67, v67, v249
	v_mul_f32_e32 v68, v68, v140
	v_mul_f32_e32 v69, v69, v141
	v_cvt_pk_bf16_f32 v192, v70, v71
	v_cvt_pk_bf16_f32 v193, v72, v73
	v_cvt_pk_bf16_f32 v194, v66, v67
	v_cvt_pk_bf16_f32 v195, v68, v69
	global_store_dwordx4 v143, v[192:195], s[16:17] offset:256
	v_add_u32_e32 v143, 0x50000, v143
	s_waitcnt vmcnt(15)
	v_lshlrev_b32_e32 v244, 16, v196
	v_and_b32_e32 v245, 0xffff0000, v196
	v_lshlrev_b32_e32 v246, 16, v197
	v_and_b32_e32 v247, 0xffff0000, v197
	v_lshlrev_b32_e32 v248, 16, v198
	v_and_b32_e32 v249, 0xffff0000, v198
	v_lshlrev_b32_e32 v140, 16, v199
	v_and_b32_e32 v141, 0xffff0000, v199
	v_mul_f32_e32 v62, v62, v244
	v_mul_f32_e32 v63, v63, v245
	v_mul_f32_e32 v64, v64, v246
	v_mul_f32_e32 v65, v65, v247
	v_mul_f32_e32 v58, v58, v248
	v_mul_f32_e32 v59, v59, v249
	v_mul_f32_e32 v60, v60, v140
	v_mul_f32_e32 v61, v61, v141
	v_cvt_pk_bf16_f32 v196, v62, v63
	v_cvt_pk_bf16_f32 v197, v64, v65
	v_cvt_pk_bf16_f32 v198, v58, v59
	v_cvt_pk_bf16_f32 v199, v60, v61
	global_store_dwordx4 v143, v[196:199], s[16:17]
	s_nop 0
	s_waitcnt vmcnt(15)
	v_lshlrev_b32_e32 v244, 16, v224
	v_and_b32_e32 v245, 0xffff0000, v224
	v_lshlrev_b32_e32 v246, 16, v225
	v_and_b32_e32 v247, 0xffff0000, v225
	v_lshlrev_b32_e32 v248, 16, v226
	v_and_b32_e32 v249, 0xffff0000, v226
	v_lshlrev_b32_e32 v140, 16, v227
	v_and_b32_e32 v141, 0xffff0000, v227
	v_mul_f32_e32 v30, v30, v244
	v_mul_f32_e32 v31, v31, v245
	v_mul_f32_e32 v32, v32, v246
	v_mul_f32_e32 v33, v33, v247
	v_mul_f32_e32 v26, v26, v248
	v_mul_f32_e32 v27, v27, v249
	v_mul_f32_e32 v28, v28, v140
	v_mul_f32_e32 v29, v29, v141
	v_cvt_pk_bf16_f32 v224, v30, v31
	v_cvt_pk_bf16_f32 v225, v32, v33
	v_cvt_pk_bf16_f32 v226, v26, v27
	v_cvt_pk_bf16_f32 v227, v28, v29
	global_store_dwordx4 v143, v[224:227], s[16:17] offset:256
	v_add_u32_e32 v143, 0x10000, v143
	s_waitcnt vmcnt(14)
	v_lshlrev_b32_e32 v244, 16, v164
	v_and_b32_e32 v245, 0xffff0000, v164
	v_lshlrev_b32_e32 v246, 16, v165
	v_and_b32_e32 v247, 0xffff0000, v165
	v_lshlrev_b32_e32 v248, 16, v166
	v_and_b32_e32 v249, 0xffff0000, v166
	v_lshlrev_b32_e32 v140, 16, v167
	v_and_b32_e32 v141, 0xffff0000, v167
	v_mul_f32_e32 v54, v54, v244
	v_mul_f32_e32 v55, v55, v245
	v_mul_f32_e32 v56, v56, v246
	v_mul_f32_e32 v57, v57, v247
	v_mul_f32_e32 v50, v50, v248
	v_mul_f32_e32 v51, v51, v249
	v_mul_f32_e32 v52, v52, v140
	v_mul_f32_e32 v53, v53, v141
	v_cvt_pk_bf16_f32 v164, v54, v55
	v_cvt_pk_bf16_f32 v165, v56, v57
	v_cvt_pk_bf16_f32 v166, v50, v51
	v_cvt_pk_bf16_f32 v167, v52, v53
	global_store_dwordx4 v143, v[164:167], s[16:17]
	s_nop 0
	s_waitcnt vmcnt(13)
	v_lshlrev_b32_e32 v244, 16, v168
	v_and_b32_e32 v245, 0xffff0000, v168
	v_lshlrev_b32_e32 v246, 16, v169
	v_and_b32_e32 v247, 0xffff0000, v169
	v_lshlrev_b32_e32 v248, 16, v170
	v_and_b32_e32 v249, 0xffff0000, v170
	v_lshlrev_b32_e32 v140, 16, v171
	v_and_b32_e32 v141, 0xffff0000, v171
	v_mul_f32_e32 v22, v22, v244
	v_mul_f32_e32 v23, v23, v245
	v_mul_f32_e32 v24, v24, v246
	v_mul_f32_e32 v25, v25, v247
	v_mul_f32_e32 v18, v18, v248
	v_mul_f32_e32 v19, v19, v249
	v_mul_f32_e32 v20, v20, v140
	v_mul_f32_e32 v21, v21, v141
	v_cvt_pk_bf16_f32 v168, v22, v23
	v_cvt_pk_bf16_f32 v169, v24, v25
	v_cvt_pk_bf16_f32 v170, v18, v19
	v_cvt_pk_bf16_f32 v171, v20, v21
	global_store_dwordx4 v143, v[168:171], s[16:17] offset:256
	v_add_u32_e32 v143, 0x10000, v143
	s_waitcnt vmcnt(12)
	v_lshlrev_b32_e32 v244, 16, v172
	v_and_b32_e32 v245, 0xffff0000, v172
	v_lshlrev_b32_e32 v246, 16, v173
	v_and_b32_e32 v247, 0xffff0000, v173
	v_lshlrev_b32_e32 v248, 16, v174
	v_and_b32_e32 v249, 0xffff0000, v174
	v_lshlrev_b32_e32 v140, 16, v175
	v_and_b32_e32 v141, 0xffff0000, v175
	v_mul_f32_e32 v46, v46, v244
	v_mul_f32_e32 v47, v47, v245
	v_mul_f32_e32 v48, v48, v246
	v_mul_f32_e32 v49, v49, v247
	v_mul_f32_e32 v42, v42, v248
	v_mul_f32_e32 v43, v43, v249
	v_mul_f32_e32 v44, v44, v140
	v_mul_f32_e32 v45, v45, v141
	v_cvt_pk_bf16_f32 v172, v46, v47
	v_cvt_pk_bf16_f32 v173, v48, v49
	v_cvt_pk_bf16_f32 v174, v42, v43
	v_cvt_pk_bf16_f32 v175, v44, v45
	global_store_dwordx4 v143, v[172:175], s[16:17]
	s_nop 0
	s_waitcnt vmcnt(11)
	v_lshlrev_b32_e32 v244, 16, v176
	v_and_b32_e32 v245, 0xffff0000, v176
	v_lshlrev_b32_e32 v246, 16, v177
	v_and_b32_e32 v247, 0xffff0000, v177
	v_lshlrev_b32_e32 v248, 16, v178
	v_and_b32_e32 v249, 0xffff0000, v178
	v_lshlrev_b32_e32 v140, 16, v179
	v_and_b32_e32 v141, 0xffff0000, v179
	v_mul_f32_e32 v14, v14, v244
	v_mul_f32_e32 v15, v15, v245
	v_mul_f32_e32 v16, v16, v246
	v_mul_f32_e32 v17, v17, v247
	v_mul_f32_e32 v10, v10, v248
	v_mul_f32_e32 v11, v11, v249
	v_mul_f32_e32 v12, v12, v140
	v_mul_f32_e32 v13, v13, v141
	v_cvt_pk_bf16_f32 v176, v14, v15
	v_cvt_pk_bf16_f32 v177, v16, v17
	v_cvt_pk_bf16_f32 v178, v10, v11
	v_cvt_pk_bf16_f32 v179, v12, v13
	global_store_dwordx4 v143, v[176:179], s[16:17] offset:256
	v_add_u32_e32 v143, 0x10000, v143
	s_waitcnt vmcnt(10)
	v_lshlrev_b32_e32 v244, 16, v180
	v_and_b32_e32 v245, 0xffff0000, v180
	v_lshlrev_b32_e32 v246, 16, v181
	v_and_b32_e32 v247, 0xffff0000, v181
	v_lshlrev_b32_e32 v248, 16, v182
	v_and_b32_e32 v249, 0xffff0000, v182
	v_lshlrev_b32_e32 v140, 16, v183
	v_and_b32_e32 v141, 0xffff0000, v183
	v_mul_f32_e32 v38, v38, v244
	v_mul_f32_e32 v39, v39, v245
	v_mul_f32_e32 v40, v40, v246
	v_mul_f32_e32 v41, v41, v247
	v_mul_f32_e32 v34, v34, v248
	v_mul_f32_e32 v35, v35, v249
	v_mul_f32_e32 v36, v36, v140
	v_mul_f32_e32 v37, v37, v141
	v_cvt_pk_bf16_f32 v180, v38, v39
	v_cvt_pk_bf16_f32 v181, v40, v41
	v_cvt_pk_bf16_f32 v182, v34, v35
	v_cvt_pk_bf16_f32 v183, v36, v37
	global_store_dwordx4 v143, v[180:183], s[16:17]
	s_nop 0
	s_waitcnt vmcnt(9)
	v_lshlrev_b32_e32 v244, 16, v184
	v_and_b32_e32 v245, 0xffff0000, v184
	v_lshlrev_b32_e32 v246, 16, v185
	v_and_b32_e32 v247, 0xffff0000, v185
	v_lshlrev_b32_e32 v248, 16, v186
	v_and_b32_e32 v249, 0xffff0000, v186
	v_lshlrev_b32_e32 v140, 16, v187
	v_and_b32_e32 v141, 0xffff0000, v187
	v_mul_f32_e32 v6, v6, v244
	v_mul_f32_e32 v7, v7, v245
	v_mul_f32_e32 v8, v8, v246
	v_mul_f32_e32 v9, v9, v247
	v_mul_f32_e32 v2, v2, v248
	v_mul_f32_e32 v3, v3, v249
	v_mul_f32_e32 v4, v4, v140
	v_mul_f32_e32 v5, v5, v141
	v_cvt_pk_bf16_f32 v184, v6, v7
	v_cvt_pk_bf16_f32 v185, v8, v9
	v_cvt_pk_bf16_f32 v186, v2, v3
	v_cvt_pk_bf16_f32 v187, v4, v5
	global_store_dwordx4 v143, v[184:187], s[16:17] offset:256
	s_nop 0

.Lout_plain:
	s_add_u32 s18, s24, 0x28064000
	s_addc_u32 s19, s25, 0
	v_mov_b32_e32 v243, v144
	global_load_dwordx4 v[156:159], v240, s[6:7]
	global_load_dwordx4 v[160:163], v240, s[6:7] offset:16
	global_load_dwordx4 v[164:167], v240, s[6:7] offset:512
	global_load_dwordx4 v[168:171], v240, s[6:7] offset:528
	v_add_u32_e32 v240, 0x20000, v240
	global_load_dwordx4 v[172:175], v240, s[6:7]
	global_load_dwordx4 v[176:179], v240, s[6:7] offset:16
	global_load_dwordx4 v[180:183], v240, s[6:7] offset:512
	global_load_dwordx4 v[184:187], v240, s[6:7] offset:528
	v_add_u32_e32 v240, 0x20000, v240
	global_load_dwordx4 v[188:191], v240, s[6:7]
	global_load_dwordx4 v[192:195], v240, s[6:7] offset:16
	global_load_dwordx4 v[196:199], v240, s[6:7] offset:512
	global_load_dwordx4 v[224:227], v240, s[6:7] offset:528
	v_add_u32_e32 v240, 0x20000, v240
	v_mov_b32_e32 v144, 0
	v_mov_b32_e32 v145, 0
	v_mov_b32_e32 v146, 0
	v_mov_b32_e32 v147, 0
	v_mov_b32_e32 v148, 0
	v_mov_b32_e32 v149, 0
	v_mov_b32_e32 v150, 0
	v_mov_b32_e32 v151, 0
	s_waitcnt vmcnt(10)
	v_pk_add_f32 v[126:127], v[126:127], v[156:157]
	v_pk_add_f32 v[128:129], v[128:129], v[158:159]
	v_pk_add_f32 v[122:123], v[122:123], v[160:161]
	v_pk_add_f32 v[124:125], v[124:125], v[162:163]
	global_load_dwordx4 v[156:159], v240, s[6:7]
	global_load_dwordx4 v[160:163], v240, s[6:7] offset:16
	v_fmac_f32_e32 v144, v126, v126
	v_fmac_f32_e32 v144, v127, v127
	v_fmac_f32_e32 v144, v128, v128
	v_fmac_f32_e32 v144, v129, v129
	v_fmac_f32_e32 v144, v122, v122
	v_fmac_f32_e32 v144, v123, v123
	v_fmac_f32_e32 v144, v124, v124
	v_fmac_f32_e32 v144, v125, v125
	s_waitcnt vmcnt(10)
	v_pk_add_f32 v[118:119], v[118:119], v[164:165]
	v_pk_add_f32 v[120:121], v[120:121], v[166:167]
	v_pk_add_f32 v[114:115], v[114:115], v[168:169]
	v_pk_add_f32 v[116:117], v[116:117], v[170:171]
	global_load_dwordx4 v[164:167], v240, s[6:7] offset:512
	global_load_dwordx4 v[168:171], v240, s[6:7] offset:528
	v_add_u32_e32 v240, 0xa0000, v240
	v_fmac_f32_e32 v144, v118, v118
	v_fmac_f32_e32 v144, v119, v119
	v_fmac_f32_e32 v144, v120, v120
	v_fmac_f32_e32 v144, v121, v121
	v_fmac_f32_e32 v144, v114, v114
	v_fmac_f32_e32 v144, v115, v115
	v_fmac_f32_e32 v144, v116, v116
	v_fmac_f32_e32 v144, v117, v117
	s_waitcnt vmcnt(10)
	v_pk_add_f32 v[110:111], v[110:111], v[172:173]
	v_pk_add_f32 v[112:113], v[112:113], v[174:175]
	v_pk_add_f32 v[106:107], v[106:107], v[176:177]
	v_pk_add_f32 v[108:109], v[108:109], v[178:179]
	global_load_dwordx4 v[172:175], v240, s[6:7]
	global_load_dwordx4 v[176:179], v240, s[6:7] offset:16
	v_fmac_f32_e32 v145, v110, v110
	v_fmac_f32_e32 v145, v111, v111
	v_fmac_f32_e32 v145, v112, v112
	v_fmac_f32_e32 v145, v113, v113
	v_fmac_f32_e32 v145, v106, v106
	v_fmac_f32_e32 v145, v107, v107
	v_fmac_f32_e32 v145, v108, v108
	v_fmac_f32_e32 v145, v109, v109
	s_waitcnt vmcnt(10)
	v_pk_add_f32 v[102:103], v[102:103], v[180:181]
	v_pk_add_f32 v[104:105], v[104:105], v[182:183]
	v_pk_add_f32 v[98:99], v[98:99], v[184:185]
	v_pk_add_f32 v[100:101], v[100:101], v[186:187]
	global_load_dwordx4 v[180:183], v240, s[6:7] offset:512
	global_load_dwordx4 v[184:187], v240, s[6:7] offset:528
	v_add_u32_e32 v240, 0x20000, v240
	v_fmac_f32_e32 v145, v102, v102
	v_fmac_f32_e32 v145, v103, v103
	v_fmac_f32_e32 v145, v104, v104
	v_fmac_f32_e32 v145, v105, v105
	v_fmac_f32_e32 v145, v98, v98
	v_fmac_f32_e32 v145, v99, v99
	v_fmac_f32_e32 v145, v100, v100
	v_fmac_f32_e32 v145, v101, v101
	s_waitcnt vmcnt(10)
	v_pk_add_f32 v[94:95], v[94:95], v[188:189]
	v_pk_add_f32 v[96:97], v[96:97], v[190:191]
	v_pk_add_f32 v[90:91], v[90:91], v[192:193]
	v_pk_add_f32 v[92:93], v[92:93], v[194:195]
	global_load_dwordx4 v[188:191], v240, s[6:7]
	global_load_dwordx4 v[192:195], v240, s[6:7] offset:16
	v_fmac_f32_e32 v146, v94, v94
	v_fmac_f32_e32 v146, v95, v95
	v_fmac_f32_e32 v146, v96, v96
	v_fmac_f32_e32 v146, v97, v97
	v_fmac_f32_e32 v146, v90, v90
	v_fmac_f32_e32 v146, v91, v91
	v_fmac_f32_e32 v146, v92, v92
	v_fmac_f32_e32 v146, v93, v93
	s_waitcnt vmcnt(10)
	v_pk_add_f32 v[86:87], v[86:87], v[196:197]
	v_pk_add_f32 v[88:89], v[88:89], v[198:199]
	v_pk_add_f32 v[82:83], v[82:83], v[224:225]
	v_pk_add_f32 v[84:85], v[84:85], v[226:227]
	global_load_dwordx4 v[196:199], v240, s[6:7] offset:512
	global_load_dwordx4 v[224:227], v240, s[6:7] offset:528
	v_add_u32_e32 v240, 0x20000, v240
	v_fmac_f32_e32 v146, v86, v86
	v_fmac_f32_e32 v146, v87, v87
	v_fmac_f32_e32 v146, v88, v88
	v_fmac_f32_e32 v146, v89, v89
	v_fmac_f32_e32 v146, v82, v82
	v_fmac_f32_e32 v146, v83, v83
	v_fmac_f32_e32 v146, v84, v84
	v_fmac_f32_e32 v146, v85, v85
	s_waitcnt vmcnt(10)
	v_pk_add_f32 v[78:79], v[78:79], v[156:157]
	v_pk_add_f32 v[80:81], v[80:81], v[158:159]
	v_pk_add_f32 v[74:75], v[74:75], v[160:161]
	v_pk_add_f32 v[76:77], v[76:77], v[162:163]
	global_load_dwordx4 v[156:159], v240, s[6:7]
	global_load_dwordx4 v[160:163], v240, s[6:7] offset:16
	v_fmac_f32_e32 v147, v78, v78
	v_fmac_f32_e32 v147, v79, v79
	v_fmac_f32_e32 v147, v80, v80
	v_fmac_f32_e32 v147, v81, v81
	v_fmac_f32_e32 v147, v74, v74
	v_fmac_f32_e32 v147, v75, v75
	v_fmac_f32_e32 v147, v76, v76
	v_fmac_f32_e32 v147, v77, v77
	s_waitcnt vmcnt(10)
	v_pk_add_f32 v[70:71], v[70:71], v[164:165]
	v_pk_add_f32 v[72:73], v[72:73], v[166:167]
	v_pk_add_f32 v[66:67], v[66:67], v[168:169]
	v_pk_add_f32 v[68:69], v[68:69], v[170:171]
	global_load_dwordx4 v[164:167], v240, s[6:7] offset:512
	global_load_dwordx4 v[168:171], v240, s[6:7] offset:528
	v_add_u32_e32 v240, 0x20000, v240
	v_fmac_f32_e32 v147, v70, v70
	v_fmac_f32_e32 v147, v71, v71
	v_fmac_f32_e32 v147, v72, v72
	v_fmac_f32_e32 v147, v73, v73
	v_fmac_f32_e32 v147, v66, v66
	v_fmac_f32_e32 v147, v67, v67
	v_fmac_f32_e32 v147, v68, v68
	v_fmac_f32_e32 v147, v69, v69
	s_waitcnt vmcnt(10)
	v_pk_add_f32 v[62:63], v[62:63], v[172:173]
	v_pk_add_f32 v[64:65], v[64:65], v[174:175]
	v_pk_add_f32 v[58:59], v[58:59], v[176:177]
	v_pk_add_f32 v[60:61], v[60:61], v[178:179]
	global_load_dwordx4 v[172:175], v240, s[6:7]
	global_load_dwordx4 v[176:179], v240, s[6:7] offset:16
	v_fmac_f32_e32 v148, v62, v62
	v_fmac_f32_e32 v148, v63, v63
	v_fmac_f32_e32 v148, v64, v64
	v_fmac_f32_e32 v148, v65, v65
	v_fmac_f32_e32 v148, v58, v58
	v_fmac_f32_e32 v148, v59, v59
	v_fmac_f32_e32 v148, v60, v60
	v_fmac_f32_e32 v148, v61, v61
	s_waitcnt vmcnt(10)
	v_pk_add_f32 v[54:55], v[54:55], v[180:181]
	v_pk_add_f32 v[56:57], v[56:57], v[182:183]
	v_pk_add_f32 v[50:51], v[50:51], v[184:185]
	v_pk_add_f32 v[52:53], v[52:53], v[186:187]
	global_load_dwordx4 v[180:183], v240, s[6:7] offset:512
	global_load_dwordx4 v[184:187], v240, s[6:7] offset:528
	v_fmac_f32_e32 v148, v54, v54
	v_fmac_f32_e32 v148, v55, v55
	v_fmac_f32_e32 v148, v56, v56
	v_fmac_f32_e32 v148, v57, v57
	v_fmac_f32_e32 v148, v50, v50
	v_fmac_f32_e32 v148, v51, v51
	v_fmac_f32_e32 v148, v52, v52
	v_fmac_f32_e32 v148, v53, v53
	s_waitcnt vmcnt(10)
	v_pk_add_f32 v[46:47], v[46:47], v[188:189]
	v_pk_add_f32 v[48:49], v[48:49], v[190:191]
	v_pk_add_f32 v[42:43], v[42:43], v[192:193]
	v_pk_add_f32 v[44:45], v[44:45], v[194:195]
	v_fmac_f32_e32 v149, v46, v46
	v_fmac_f32_e32 v149, v47, v47
	v_fmac_f32_e32 v149, v48, v48
	v_fmac_f32_e32 v149, v49, v49
	v_fmac_f32_e32 v149, v42, v42
	v_fmac_f32_e32 v149, v43, v43
	v_fmac_f32_e32 v149, v44, v44
	v_fmac_f32_e32 v149, v45, v45
	s_waitcnt vmcnt(8)
	v_pk_add_f32 v[38:39], v[38:39], v[196:197]
	v_pk_add_f32 v[40:41], v[40:41], v[198:199]
	v_pk_add_f32 v[34:35], v[34:35], v[224:225]
	v_pk_add_f32 v[36:37], v[36:37], v[226:227]
	v_fmac_f32_e32 v149, v38, v38
	v_fmac_f32_e32 v149, v39, v39
	v_fmac_f32_e32 v149, v40, v40
	v_fmac_f32_e32 v149, v41, v41
	v_fmac_f32_e32 v149, v34, v34
	v_fmac_f32_e32 v149, v35, v35
	v_fmac_f32_e32 v149, v36, v36
	v_fmac_f32_e32 v149, v37, v37
	s_waitcnt vmcnt(6)
	v_pk_add_f32 v[30:31], v[30:31], v[156:157]
	v_pk_add_f32 v[32:33], v[32:33], v[158:159]
	v_pk_add_f32 v[26:27], v[26:27], v[160:161]
	v_pk_add_f32 v[28:29], v[28:29], v[162:163]
	v_fmac_f32_e32 v150, v30, v30
	v_fmac_f32_e32 v150, v31, v31
	v_fmac_f32_e32 v150, v32, v32
	v_fmac_f32_e32 v150, v33, v33
	v_fmac_f32_e32 v150, v26, v26
	v_fmac_f32_e32 v150, v27, v27
	v_fmac_f32_e32 v150, v28, v28
	v_fmac_f32_e32 v150, v29, v29
	s_waitcnt vmcnt(4)
	v_pk_add_f32 v[22:23], v[22:23], v[164:165]
	v_pk_add_f32 v[24:25], v[24:25], v[166:167]
	v_pk_add_f32 v[18:19], v[18:19], v[168:169]
	v_pk_add_f32 v[20:21], v[20:21], v[170:171]
	v_fmac_f32_e32 v150, v22, v22
	v_fmac_f32_e32 v150, v23, v23
	v_fmac_f32_e32 v150, v24, v24
	v_fmac_f32_e32 v150, v25, v25
	v_fmac_f32_e32 v150, v18, v18
	v_fmac_f32_e32 v150, v19, v19
	v_fmac_f32_e32 v150, v20, v20
	v_fmac_f32_e32 v150, v21, v21
	s_waitcnt vmcnt(2)
	v_pk_add_f32 v[14:15], v[14:15], v[172:173]
	v_pk_add_f32 v[16:17], v[16:17], v[174:175]
	v_pk_add_f32 v[10:11], v[10:11], v[176:177]
	v_pk_add_f32 v[12:13], v[12:13], v[178:179]
	v_fmac_f32_e32 v151, v14, v14
	v_fmac_f32_e32 v151, v15, v15
	v_fmac_f32_e32 v151, v16, v16
	v_fmac_f32_e32 v151, v17, v17
	v_fmac_f32_e32 v151, v10, v10
	v_fmac_f32_e32 v151, v11, v11
	v_fmac_f32_e32 v151, v12, v12
	v_fmac_f32_e32 v151, v13, v13
	s_waitcnt vmcnt(0)
	v_pk_add_f32 v[6:7], v[6:7], v[180:181]
	v_pk_add_f32 v[8:9], v[8:9], v[182:183]
	v_pk_add_f32 v[2:3], v[2:3], v[184:185]
	v_pk_add_f32 v[4:5], v[4:5], v[186:187]
	v_fmac_f32_e32 v151, v6, v6
	v_fmac_f32_e32 v151, v7, v7
	v_fmac_f32_e32 v151, v8, v8
	v_fmac_f32_e32 v151, v9, v9
	v_fmac_f32_e32 v151, v2, v2
	v_fmac_f32_e32 v151, v3, v3
	v_fmac_f32_e32 v151, v4, v4
	v_fmac_f32_e32 v151, v5, v5
	v_xor_b32_e32 v156, 16, v217
	v_xor_b32_e32 v157, 32, v217
	v_lshlrev_b32_e32 v156, 2, v156
	v_lshlrev_b32_e32 v157, 2, v157
	v_lshl_add_u32 v242, s40, 8, v152
	v_lshlrev_b32_e32 v242, 2, v242
	ds_bpermute_b32 v160, v156, v144
	ds_bpermute_b32 v161, v156, v145
	ds_bpermute_b32 v162, v156, v146
	ds_bpermute_b32 v163, v156, v147
	ds_bpermute_b32 v164, v156, v148
	ds_bpermute_b32 v165, v156, v149
	ds_bpermute_b32 v166, v156, v150
	ds_bpermute_b32 v167, v156, v151
	s_waitcnt lgkmcnt(0)
	v_add_f32_e32 v144, v144, v160
	v_add_f32_e32 v145, v145, v161
	v_add_f32_e32 v146, v146, v162
	v_add_f32_e32 v147, v147, v163
	v_add_f32_e32 v148, v148, v164
	v_add_f32_e32 v149, v149, v165
	v_add_f32_e32 v150, v150, v166
	v_add_f32_e32 v151, v151, v167
	ds_bpermute_b32 v160, v157, v144
	ds_bpermute_b32 v161, v157, v145
	ds_bpermute_b32 v162, v157, v146
	ds_bpermute_b32 v163, v157, v147
	ds_bpermute_b32 v164, v157, v148
	ds_bpermute_b32 v165, v157, v149
	ds_bpermute_b32 v166, v157, v150
	ds_bpermute_b32 v167, v157, v151
	s_waitcnt lgkmcnt(0)
	v_add_f32_e32 v144, v144, v160
	v_add_f32_e32 v145, v145, v161
	v_add_f32_e32 v146, v146, v162
	v_add_f32_e32 v147, v147, v163
	v_add_f32_e32 v148, v148, v164
	v_add_f32_e32 v149, v149, v165
	v_add_f32_e32 v150, v150, v166
	v_add_f32_e32 v151, v151, v167
	s_and_saveexec_b64 s[2:3], s[0:1]
	global_atomic_add_f32 v242, v144, s[18:19]
	global_atomic_add_f32 v242, v145, s[18:19] offset:64
	global_atomic_add_f32 v242, v146, s[18:19] offset:128
	global_atomic_add_f32 v242, v147, s[18:19] offset:192
	global_atomic_add_f32 v242, v148, s[18:19] offset:512
	global_atomic_add_f32 v242, v149, s[18:19] offset:576
	global_atomic_add_f32 v242, v150, s[18:19] offset:640
	global_atomic_add_f32 v242, v151, s[18:19] offset:704
	s_or_b64 exec, exec, s[2:3]
	v_mov_b32_e32 v172, v2
	v_mov_b32_e32 v173, v3
	v_mov_b32_e32 v174, v4
	v_mov_b32_e32 v175, v5
	v_mov_b32_e32 v176, v6
	v_mov_b32_e32 v177, v7
	v_mov_b32_e32 v178, v8
	v_mov_b32_e32 v179, v9
	v_mov_b32_e32 v180, v10
	v_mov_b32_e32 v181, v11
	v_mov_b32_e32 v182, v12
	v_mov_b32_e32 v183, v13
	v_mov_b32_e32 v184, v14
	v_mov_b32_e32 v185, v15
	v_mov_b32_e32 v186, v16
	v_mov_b32_e32 v187, v17

.LBB0_1166:
	s_add_u32 s4, s24, 0x28064000
	s_addc_u32 s5, s25, 0
	v_readlane_b32 s8, v250, 2
	v_readlane_b32 s9, v250, 3
	v_readlane_b32 s10, v250, 4
	v_readlane_b32 s11, v250, 5
	s_mov_b32 s12, 0xf800000
	v_mov_b32_e32 v188, 0x358637bd
	v_mov_b32_e32 v189, 0x260
	s_nop 1
	global_load_dword v144, v242, s[4:5]
	global_load_dword v145, v242, s[4:5] offset:64
	global_load_dword v146, v242, s[4:5] offset:128
	global_load_dword v147, v242, s[4:5] offset:192
	global_load_dword v148, v242, s[4:5] offset:512
	global_load_dword v149, v242, s[4:5] offset:576
	global_load_dword v150, v242, s[4:5] offset:640
	global_load_dword v151, v242, s[4:5] offset:704
	global_load_dwordx4 v[228:231], v243, s[8:9]
	global_load_dwordx4 v[232:235], v243, s[8:9] offset:16
	global_load_dwordx4 v[236:239], v243, s[8:9] offset:512
	global_load_dwordx4 v[140:143], v243, s[8:9] offset:528
	v_mov_b32_e32 v2, v172
	v_mov_b32_e32 v3, v173
	v_mov_b32_e32 v4, v174
	v_mov_b32_e32 v5, v175
	v_mov_b32_e32 v6, v176
	v_mov_b32_e32 v7, v177
	v_mov_b32_e32 v8, v178
	v_mov_b32_e32 v9, v179
	v_mov_b32_e32 v10, v180
	v_mov_b32_e32 v11, v181
	v_mov_b32_e32 v12, v182
	v_mov_b32_e32 v13, v183
	v_mov_b32_e32 v14, v184
	v_mov_b32_e32 v15, v185
	v_mov_b32_e32 v16, v186
	v_mov_b32_e32 v17, v187
	s_waitcnt vmcnt(4)
	v_fmamk_f32 v144, v144, 0x3a000000, v188
	v_mul_f32_e32 v190, 0x4f800000, v144
	v_cmp_gt_f32_e32 vcc, s12, v144
	s_nop 1
	v_cndmask_b32_e32 v144, v144, v190, vcc
	v_sqrt_f32_e32 v190, v144
	s_nop 0
	v_add_u32_e32 v191, -1, v190
	v_add_u32_e32 v192, 1, v190
	v_fma_f32 v193, -v191, v190, v144
	v_fma_f32 v194, -v192, v190, v144
	v_cmp_ge_f32_e64 s[0:1], 0, v193
	s_nop 1
	v_cndmask_b32_e64 v190, v190, v191, s[0:1]
	v_cmp_lt_f32_e64 s[0:1], 0, v194
	s_nop 1
	v_cndmask_b32_e64 v190, v190, v192, s[0:1]
	v_mul_f32_e32 v191, 0x37800000, v190
	v_cndmask_b32_e32 v190, v190, v191, vcc
	v_cmp_class_f32_e32 vcc, v144, v189
	s_nop 1
	v_cndmask_b32_e32 v144, v190, v144, vcc
	v_div_scale_f32 v190, s[0:1], v144, v144, 1.0
	v_rcp_f32_e32 v192, v190
	v_div_scale_f32 v191, vcc, 1.0, v144, 1.0
	v_fma_f32 v193, -v190, v192, 1.0
	v_fmac_f32_e32 v192, v193, v192
	v_mul_f32_e32 v193, v191, v192
	v_fma_f32 v194, -v190, v193, v191
	v_fmac_f32_e32 v193, v194, v192
	v_fma_f32 v190, -v190, v193, v191
	v_div_fmas_f32 v190, v190, v192, v193
	v_div_fixup_f32 v144, v190, v144, 1.0
	v_fmamk_f32 v145, v145, 0x3a000000, v188
	v_mul_f32_e32 v190, 0x4f800000, v145
	v_cmp_gt_f32_e32 vcc, s12, v145
	s_nop 1
	v_cndmask_b32_e32 v145, v145, v190, vcc
	v_sqrt_f32_e32 v190, v145
	s_nop 0
	v_add_u32_e32 v191, -1, v190
	v_add_u32_e32 v192, 1, v190
	v_fma_f32 v193, -v191, v190, v145
	v_fma_f32 v194, -v192, v190, v145
	v_cmp_ge_f32_e64 s[0:1], 0, v193
	s_nop 1
	v_cndmask_b32_e64 v190, v190, v191, s[0:1]
	v_cmp_lt_f32_e64 s[0:1], 0, v194
	s_nop 1
	v_cndmask_b32_e64 v190, v190, v192, s[0:1]
	v_mul_f32_e32 v191, 0x37800000, v190
	v_cndmask_b32_e32 v190, v190, v191, vcc
	v_cmp_class_f32_e32 vcc, v145, v189
	s_nop 1
	v_cndmask_b32_e32 v145, v190, v145, vcc
	v_div_scale_f32 v190, s[0:1], v145, v145, 1.0
	v_rcp_f32_e32 v192, v190
	v_div_scale_f32 v191, vcc, 1.0, v145, 1.0
	v_fma_f32 v193, -v190, v192, 1.0
	v_fmac_f32_e32 v192, v193, v192
	v_mul_f32_e32 v193, v191, v192
	v_fma_f32 v194, -v190, v193, v191
	v_fmac_f32_e32 v193, v194, v192
	v_fma_f32 v190, -v190, v193, v191
	v_div_fmas_f32 v190, v190, v192, v193
	v_div_fixup_f32 v145, v190, v145, 1.0
	v_fmamk_f32 v146, v146, 0x3a000000, v188
	v_mul_f32_e32 v190, 0x4f800000, v146
	v_cmp_gt_f32_e32 vcc, s12, v146
	s_nop 1
	v_cndmask_b32_e32 v146, v146, v190, vcc
	v_sqrt_f32_e32 v190, v146
	s_nop 0
	v_add_u32_e32 v191, -1, v190
	v_add_u32_e32 v192, 1, v190
	v_fma_f32 v193, -v191, v190, v146
	v_fma_f32 v194, -v192, v190, v146
	v_cmp_ge_f32_e64 s[0:1], 0, v193
	s_nop 1
	v_cndmask_b32_e64 v190, v190, v191, s[0:1]
	v_cmp_lt_f32_e64 s[0:1], 0, v194
	s_nop 1
	v_cndmask_b32_e64 v190, v190, v192, s[0:1]
	v_mul_f32_e32 v191, 0x37800000, v190
	v_cndmask_b32_e32 v190, v190, v191, vcc
	v_cmp_class_f32_e32 vcc, v146, v189
	s_nop 1
	v_cndmask_b32_e32 v146, v190, v146, vcc
	v_div_scale_f32 v190, s[0:1], v146, v146, 1.0
	v_rcp_f32_e32 v192, v190
	v_div_scale_f32 v191, vcc, 1.0, v146, 1.0
	v_fma_f32 v193, -v190, v192, 1.0
	v_fmac_f32_e32 v192, v193, v192
	v_mul_f32_e32 v193, v191, v192
	v_fma_f32 v194, -v190, v193, v191
	v_fmac_f32_e32 v193, v194, v192
	v_fma_f32 v190, -v190, v193, v191
	v_div_fmas_f32 v190, v190, v192, v193
	v_div_fixup_f32 v146, v190, v146, 1.0
	v_fmamk_f32 v147, v147, 0x3a000000, v188
	v_mul_f32_e32 v190, 0x4f800000, v147
	v_cmp_gt_f32_e32 vcc, s12, v147
	s_nop 1
	v_cndmask_b32_e32 v147, v147, v190, vcc
	v_sqrt_f32_e32 v190, v147
	s_nop 0
	v_add_u32_e32 v191, -1, v190
	v_add_u32_e32 v192, 1, v190
	v_fma_f32 v193, -v191, v190, v147
	v_fma_f32 v194, -v192, v190, v147
	v_cmp_ge_f32_e64 s[0:1], 0, v193
	s_nop 1
	v_cndmask_b32_e64 v190, v190, v191, s[0:1]
	v_cmp_lt_f32_e64 s[0:1], 0, v194
	s_nop 1
	v_cndmask_b32_e64 v190, v190, v192, s[0:1]
	v_mul_f32_e32 v191, 0x37800000, v190
	v_cndmask_b32_e32 v190, v190, v191, vcc
	v_cmp_class_f32_e32 vcc, v147, v189
	s_nop 1
	v_cndmask_b32_e32 v147, v190, v147, vcc
	v_div_scale_f32 v190, s[0:1], v147, v147, 1.0
	v_rcp_f32_e32 v192, v190
	v_div_scale_f32 v191, vcc, 1.0, v147, 1.0
	v_fma_f32 v193, -v190, v192, 1.0
	v_fmac_f32_e32 v192, v193, v192
	v_mul_f32_e32 v193, v191, v192
	v_fma_f32 v194, -v190, v193, v191
	v_fmac_f32_e32 v193, v194, v192
	v_fma_f32 v190, -v190, v193, v191
	v_div_fmas_f32 v190, v190, v192, v193
	v_div_fixup_f32 v147, v190, v147, 1.0
	v_fmamk_f32 v148, v148, 0x3a000000, v188
	v_mul_f32_e32 v190, 0x4f800000, v148
	v_cmp_gt_f32_e32 vcc, s12, v148
	s_nop 1
	v_cndmask_b32_e32 v148, v148, v190, vcc
	v_sqrt_f32_e32 v190, v148
	s_nop 0
	v_add_u32_e32 v191, -1, v190
	v_add_u32_e32 v192, 1, v190
	v_fma_f32 v193, -v191, v190, v148
	v_fma_f32 v194, -v192, v190, v148
	v_cmp_ge_f32_e64 s[0:1], 0, v193
	s_nop 1
	v_cndmask_b32_e64 v190, v190, v191, s[0:1]
	v_cmp_lt_f32_e64 s[0:1], 0, v194
	s_nop 1
	v_cndmask_b32_e64 v190, v190, v192, s[0:1]
	v_mul_f32_e32 v191, 0x37800000, v190
	v_cndmask_b32_e32 v190, v190, v191, vcc
	v_cmp_class_f32_e32 vcc, v148, v189
	s_nop 1
	v_cndmask_b32_e32 v148, v190, v148, vcc
	v_div_scale_f32 v190, s[0:1], v148, v148, 1.0
	v_rcp_f32_e32 v192, v190
	v_div_scale_f32 v191, vcc, 1.0, v148, 1.0
	v_fma_f32 v193, -v190, v192, 1.0
	v_fmac_f32_e32 v192, v193, v192
	v_mul_f32_e32 v193, v191, v192
	v_fma_f32 v194, -v190, v193, v191
	v_fmac_f32_e32 v193, v194, v192
	v_fma_f32 v190, -v190, v193, v191
	v_div_fmas_f32 v190, v190, v192, v193
	v_div_fixup_f32 v148, v190, v148, 1.0
	v_fmamk_f32 v149, v149, 0x3a000000, v188
	v_mul_f32_e32 v190, 0x4f800000, v149
	v_cmp_gt_f32_e32 vcc, s12, v149
	s_nop 1
	v_cndmask_b32_e32 v149, v149, v190, vcc
	v_sqrt_f32_e32 v190, v149
	s_nop 0
	v_add_u32_e32 v191, -1, v190
	v_add_u32_e32 v192, 1, v190
	v_fma_f32 v193, -v191, v190, v149
	v_fma_f32 v194, -v192, v190, v149
	v_cmp_ge_f32_e64 s[0:1], 0, v193
	s_nop 1
	v_cndmask_b32_e64 v190, v190, v191, s[0:1]
	v_cmp_lt_f32_e64 s[0:1], 0, v194
	s_nop 1
	v_cndmask_b32_e64 v190, v190, v192, s[0:1]
	v_mul_f32_e32 v191, 0x37800000, v190
	v_cndmask_b32_e32 v190, v190, v191, vcc
	v_cmp_class_f32_e32 vcc, v149, v189
	s_nop 1
	v_cndmask_b32_e32 v149, v190, v149, vcc
	v_div_scale_f32 v190, s[0:1], v149, v149, 1.0
	v_rcp_f32_e32 v192, v190
	v_div_scale_f32 v191, vcc, 1.0, v149, 1.0
	v_fma_f32 v193, -v190, v192, 1.0
	v_fmac_f32_e32 v192, v193, v192
	v_mul_f32_e32 v193, v191, v192
	v_fma_f32 v194, -v190, v193, v191
	v_fmac_f32_e32 v193, v194, v192
	v_fma_f32 v190, -v190, v193, v191
	v_div_fmas_f32 v190, v190, v192, v193
	v_div_fixup_f32 v149, v190, v149, 1.0
	v_fmamk_f32 v150, v150, 0x3a000000, v188
	v_mul_f32_e32 v190, 0x4f800000, v150
	v_cmp_gt_f32_e32 vcc, s12, v150
	s_nop 1
	v_cndmask_b32_e32 v150, v150, v190, vcc
	v_sqrt_f32_e32 v190, v150
	s_nop 0
	v_add_u32_e32 v191, -1, v190
	v_add_u32_e32 v192, 1, v190
	v_fma_f32 v193, -v191, v190, v150
	v_fma_f32 v194, -v192, v190, v150
	v_cmp_ge_f32_e64 s[0:1], 0, v193
	s_nop 1
	v_cndmask_b32_e64 v190, v190, v191, s[0:1]
	v_cmp_lt_f32_e64 s[0:1], 0, v194
	s_nop 1
	v_cndmask_b32_e64 v190, v190, v192, s[0:1]
	v_mul_f32_e32 v191, 0x37800000, v190
	v_cndmask_b32_e32 v190, v190, v191, vcc
	v_cmp_class_f32_e32 vcc, v150, v189
	s_nop 1
	v_cndmask_b32_e32 v150, v190, v150, vcc
	v_div_scale_f32 v190, s[0:1], v150, v150, 1.0
	v_rcp_f32_e32 v192, v190
	v_div_scale_f32 v191, vcc, 1.0, v150, 1.0
	v_fma_f32 v193, -v190, v192, 1.0
	v_fmac_f32_e32 v192, v193, v192
	v_mul_f32_e32 v193, v191, v192
	v_fma_f32 v194, -v190, v193, v191
	v_fmac_f32_e32 v193, v194, v192
	v_fma_f32 v190, -v190, v193, v191
	v_div_fmas_f32 v190, v190, v192, v193
	v_div_fixup_f32 v150, v190, v150, 1.0
	v_fmamk_f32 v151, v151, 0x3a000000, v188
	v_mul_f32_e32 v190, 0x4f800000, v151
	v_cmp_gt_f32_e32 vcc, s12, v151
	s_nop 1
	v_cndmask_b32_e32 v151, v151, v190, vcc
	v_sqrt_f32_e32 v190, v151
	s_nop 0
	v_add_u32_e32 v191, -1, v190
	v_add_u32_e32 v192, 1, v190
	v_fma_f32 v193, -v191, v190, v151
	v_fma_f32 v194, -v192, v190, v151
	v_cmp_ge_f32_e64 s[0:1], 0, v193
	s_nop 1
	v_cndmask_b32_e64 v190, v190, v191, s[0:1]
	v_cmp_lt_f32_e64 s[0:1], 0, v194
	s_nop 1
	v_cndmask_b32_e64 v190, v190, v192, s[0:1]
	v_mul_f32_e32 v191, 0x37800000, v190
	v_cndmask_b32_e32 v190, v190, v191, vcc
	v_cmp_class_f32_e32 vcc, v151, v189
	s_nop 1
	v_cndmask_b32_e32 v151, v190, v151, vcc
	v_div_scale_f32 v190, s[0:1], v151, v151, 1.0
	v_rcp_f32_e32 v192, v190
	v_div_scale_f32 v191, vcc, 1.0, v151, 1.0
	v_fma_f32 v193, -v190, v192, 1.0
	v_fmac_f32_e32 v192, v193, v192
	v_mul_f32_e32 v193, v191, v192
	v_fma_f32 v194, -v190, v193, v191
	v_fmac_f32_e32 v193, v194, v192
	v_fma_f32 v190, -v190, v193, v191
	v_div_fmas_f32 v190, v190, v192, v193
	v_div_fixup_f32 v151, v190, v151, 1.0
	s_waitcnt vmcnt(0)
	v_mul_f32_e32 v126, v126, v144
	v_mul_f32_e32 v127, v127, v144
	v_mul_f32_e32 v128, v128, v144
	v_mul_f32_e32 v129, v129, v144
	v_mul_f32_e32 v122, v122, v144
	v_mul_f32_e32 v123, v123, v144
	v_mul_f32_e32 v124, v124, v144
	v_mul_f32_e32 v125, v125, v144
	v_pk_mul_f32 v[126:127], v[126:127], v[228:229]
	v_pk_mul_f32 v[128:129], v[128:129], v[230:231]
	v_pk_mul_f32 v[122:123], v[122:123], v[232:233]
	v_pk_mul_f32 v[124:125], v[124:125], v[234:235]
	global_store_dwordx4 v241, v[126:129], s[10:11] nt
	global_store_dwordx4 v241, v[122:125], s[10:11] offset:16 nt
	v_mul_f32_e32 v118, v118, v144
	v_mul_f32_e32 v119, v119, v144
	v_mul_f32_e32 v120, v120, v144
	v_mul_f32_e32 v121, v121, v144
	v_mul_f32_e32 v114, v114, v144
	v_mul_f32_e32 v115, v115, v144
	v_mul_f32_e32 v116, v116, v144
	v_mul_f32_e32 v117, v117, v144
	v_pk_mul_f32 v[118:119], v[118:119], v[236:237]
	v_pk_mul_f32 v[120:121], v[120:121], v[238:239]
	v_pk_mul_f32 v[114:115], v[114:115], v[140:141]
	v_pk_mul_f32 v[116:117], v[116:117], v[142:143]
	global_store_dwordx4 v241, v[118:121], s[10:11] offset:512 nt
	global_store_dwordx4 v241, v[114:117], s[10:11] offset:528 nt
	v_add_u32_e32 v241, 0x20000, v241
	v_mul_f32_e32 v110, v110, v145
	v_mul_f32_e32 v111, v111, v145
	v_mul_f32_e32 v112, v112, v145
	v_mul_f32_e32 v113, v113, v145
	v_mul_f32_e32 v106, v106, v145
	v_mul_f32_e32 v107, v107, v145
	v_mul_f32_e32 v108, v108, v145
	v_mul_f32_e32 v109, v109, v145
	v_pk_mul_f32 v[110:111], v[110:111], v[228:229]
	v_pk_mul_f32 v[112:113], v[112:113], v[230:231]
	v_pk_mul_f32 v[106:107], v[106:107], v[232:233]
	v_pk_mul_f32 v[108:109], v[108:109], v[234:235]
	global_store_dwordx4 v241, v[110:113], s[10:11] nt
	global_store_dwordx4 v241, v[106:109], s[10:11] offset:16 nt
	v_mul_f32_e32 v102, v102, v145
	v_mul_f32_e32 v103, v103, v145
	v_mul_f32_e32 v104, v104, v145
	v_mul_f32_e32 v105, v105, v145
	v_mul_f32_e32 v98, v98, v145
	v_mul_f32_e32 v99, v99, v145
	v_mul_f32_e32 v100, v100, v145
	v_mul_f32_e32 v101, v101, v145
	v_pk_mul_f32 v[102:103], v[102:103], v[236:237]
	v_pk_mul_f32 v[104:105], v[104:105], v[238:239]
	v_pk_mul_f32 v[98:99], v[98:99], v[140:141]
	v_pk_mul_f32 v[100:101], v[100:101], v[142:143]
	global_store_dwordx4 v241, v[102:105], s[10:11] offset:512 nt
	global_store_dwordx4 v241, v[98:101], s[10:11] offset:528 nt
	v_add_u32_e32 v241, 0x20000, v241
	v_mul_f32_e32 v94, v94, v146
	v_mul_f32_e32 v95, v95, v146
	v_mul_f32_e32 v96, v96, v146
	v_mul_f32_e32 v97, v97, v146
	v_mul_f32_e32 v90, v90, v146
	v_mul_f32_e32 v91, v91, v146
	v_mul_f32_e32 v92, v92, v146
	v_mul_f32_e32 v93, v93, v146
	v_pk_mul_f32 v[94:95], v[94:95], v[228:229]
	v_pk_mul_f32 v[96:97], v[96:97], v[230:231]
	v_pk_mul_f32 v[90:91], v[90:91], v[232:233]
	v_pk_mul_f32 v[92:93], v[92:93], v[234:235]
	global_store_dwordx4 v241, v[94:97], s[10:11] nt
	global_store_dwordx4 v241, v[90:93], s[10:11] offset:16 nt
	v_mul_f32_e32 v86, v86, v146
	v_mul_f32_e32 v87, v87, v146
	v_mul_f32_e32 v88, v88, v146
	v_mul_f32_e32 v89, v89, v146
	v_mul_f32_e32 v82, v82, v146
	v_mul_f32_e32 v83, v83, v146
	v_mul_f32_e32 v84, v84, v146
	v_mul_f32_e32 v85, v85, v146
	v_pk_mul_f32 v[86:87], v[86:87], v[236:237]
	v_pk_mul_f32 v[88:89], v[88:89], v[238:239]
	v_pk_mul_f32 v[82:83], v[82:83], v[140:141]
	v_pk_mul_f32 v[84:85], v[84:85], v[142:143]
	global_store_dwordx4 v241, v[86:89], s[10:11] offset:512 nt
	global_store_dwordx4 v241, v[82:85], s[10:11] offset:528 nt
	v_add_u32_e32 v241, 0x20000, v241
	v_mul_f32_e32 v78, v78, v147
	v_mul_f32_e32 v79, v79, v147
	v_mul_f32_e32 v80, v80, v147
	v_mul_f32_e32 v81, v81, v147
	v_mul_f32_e32 v74, v74, v147
	v_mul_f32_e32 v75, v75, v147
	v_mul_f32_e32 v76, v76, v147
	v_mul_f32_e32 v77, v77, v147
	v_pk_mul_f32 v[78:79], v[78:79], v[228:229]
	v_pk_mul_f32 v[80:81], v[80:81], v[230:231]
	v_pk_mul_f32 v[74:75], v[74:75], v[232:233]
	v_pk_mul_f32 v[76:77], v[76:77], v[234:235]
	global_store_dwordx4 v241, v[78:81], s[10:11] nt
	global_store_dwordx4 v241, v[74:77], s[10:11] offset:16 nt
	v_mul_f32_e32 v70, v70, v147
	v_mul_f32_e32 v71, v71, v147
	v_mul_f32_e32 v72, v72, v147
	v_mul_f32_e32 v73, v73, v147
	v_mul_f32_e32 v66, v66, v147
	v_mul_f32_e32 v67, v67, v147
	v_mul_f32_e32 v68, v68, v147
	v_mul_f32_e32 v69, v69, v147
	v_pk_mul_f32 v[70:71], v[70:71], v[236:237]
	v_pk_mul_f32 v[72:73], v[72:73], v[238:239]
	v_pk_mul_f32 v[66:67], v[66:67], v[140:141]
	v_pk_mul_f32 v[68:69], v[68:69], v[142:143]
	global_store_dwordx4 v241, v[70:73], s[10:11] offset:512 nt
	global_store_dwordx4 v241, v[66:69], s[10:11] offset:528 nt
	v_add_u32_e32 v241, 0xa0000, v241
	v_mul_f32_e32 v62, v62, v148
	v_mul_f32_e32 v63, v63, v148
	v_mul_f32_e32 v64, v64, v148
	v_mul_f32_e32 v65, v65, v148
	v_mul_f32_e32 v58, v58, v148
	v_mul_f32_e32 v59, v59, v148
	v_mul_f32_e32 v60, v60, v148
	v_mul_f32_e32 v61, v61, v148
	v_pk_mul_f32 v[62:63], v[62:63], v[228:229]
	v_pk_mul_f32 v[64:65], v[64:65], v[230:231]
	v_pk_mul_f32 v[58:59], v[58:59], v[232:233]
	v_pk_mul_f32 v[60:61], v[60:61], v[234:235]
	global_store_dwordx4 v241, v[62:65], s[10:11] nt
	global_store_dwordx4 v241, v[58:61], s[10:11] offset:16 nt
	v_mul_f32_e32 v54, v54, v148
	v_mul_f32_e32 v55, v55, v148
	v_mul_f32_e32 v56, v56, v148
	v_mul_f32_e32 v57, v57, v148
	v_mul_f32_e32 v50, v50, v148
	v_mul_f32_e32 v51, v51, v148
	v_mul_f32_e32 v52, v52, v148
	v_mul_f32_e32 v53, v53, v148
	v_pk_mul_f32 v[54:55], v[54:55], v[236:237]
	v_pk_mul_f32 v[56:57], v[56:57], v[238:239]
	v_pk_mul_f32 v[50:51], v[50:51], v[140:141]
	v_pk_mul_f32 v[52:53], v[52:53], v[142:143]
	global_store_dwordx4 v241, v[54:57], s[10:11] offset:512 nt
	global_store_dwordx4 v241, v[50:53], s[10:11] offset:528 nt
	v_add_u32_e32 v241, 0x20000, v241
	v_mul_f32_e32 v46, v46, v149
	v_mul_f32_e32 v47, v47, v149
	v_mul_f32_e32 v48, v48, v149
	v_mul_f32_e32 v49, v49, v149
	v_mul_f32_e32 v42, v42, v149
	v_mul_f32_e32 v43, v43, v149
	v_mul_f32_e32 v44, v44, v149
	v_mul_f32_e32 v45, v45, v149
	v_pk_mul_f32 v[46:47], v[46:47], v[228:229]
	v_pk_mul_f32 v[48:49], v[48:49], v[230:231]
	v_pk_mul_f32 v[42:43], v[42:43], v[232:233]
	v_pk_mul_f32 v[44:45], v[44:45], v[234:235]
	global_store_dwordx4 v241, v[46:49], s[10:11] nt
	global_store_dwordx4 v241, v[42:45], s[10:11] offset:16 nt
	v_mul_f32_e32 v38, v38, v149
	v_mul_f32_e32 v39, v39, v149
	v_mul_f32_e32 v40, v40, v149
	v_mul_f32_e32 v41, v41, v149
	v_mul_f32_e32 v34, v34, v149
	v_mul_f32_e32 v35, v35, v149
	v_mul_f32_e32 v36, v36, v149
	v_mul_f32_e32 v37, v37, v149
	v_pk_mul_f32 v[38:39], v[38:39], v[236:237]
	v_pk_mul_f32 v[40:41], v[40:41], v[238:239]
	v_pk_mul_f32 v[34:35], v[34:35], v[140:141]
	v_pk_mul_f32 v[36:37], v[36:37], v[142:143]
	global_store_dwordx4 v241, v[38:41], s[10:11] offset:512 nt
	global_store_dwordx4 v241, v[34:37], s[10:11] offset:528 nt
	v_add_u32_e32 v241, 0x20000, v241
	v_mul_f32_e32 v30, v30, v150
	v_mul_f32_e32 v31, v31, v150
	v_mul_f32_e32 v32, v32, v150
	v_mul_f32_e32 v33, v33, v150
	v_mul_f32_e32 v26, v26, v150
	v_mul_f32_e32 v27, v27, v150
	v_mul_f32_e32 v28, v28, v150
	v_mul_f32_e32 v29, v29, v150
	v_pk_mul_f32 v[30:31], v[30:31], v[228:229]
	v_pk_mul_f32 v[32:33], v[32:33], v[230:231]
	v_pk_mul_f32 v[26:27], v[26:27], v[232:233]
	v_pk_mul_f32 v[28:29], v[28:29], v[234:235]
	global_store_dwordx4 v241, v[30:33], s[10:11] nt
	global_store_dwordx4 v241, v[26:29], s[10:11] offset:16 nt
	v_mul_f32_e32 v22, v22, v150
	v_mul_f32_e32 v23, v23, v150
	v_mul_f32_e32 v24, v24, v150
	v_mul_f32_e32 v25, v25, v150
	v_mul_f32_e32 v18, v18, v150
	v_mul_f32_e32 v19, v19, v150
	v_mul_f32_e32 v20, v20, v150
	v_mul_f32_e32 v21, v21, v150
	v_pk_mul_f32 v[22:23], v[22:23], v[236:237]
	v_pk_mul_f32 v[24:25], v[24:25], v[238:239]
	v_pk_mul_f32 v[18:19], v[18:19], v[140:141]
	v_pk_mul_f32 v[20:21], v[20:21], v[142:143]
	global_store_dwordx4 v241, v[22:25], s[10:11] offset:512 nt
	global_store_dwordx4 v241, v[18:21], s[10:11] offset:528 nt
	v_add_u32_e32 v241, 0x20000, v241
	v_mul_f32_e32 v14, v14, v151
	v_mul_f32_e32 v15, v15, v151
	v_mul_f32_e32 v16, v16, v151
	v_mul_f32_e32 v17, v17, v151
	v_mul_f32_e32 v10, v10, v151
	v_mul_f32_e32 v11, v11, v151
	v_mul_f32_e32 v12, v12, v151
	v_mul_f32_e32 v13, v13, v151
	v_pk_mul_f32 v[14:15], v[14:15], v[228:229]
	v_pk_mul_f32 v[16:17], v[16:17], v[230:231]
	v_pk_mul_f32 v[10:11], v[10:11], v[232:233]
	v_pk_mul_f32 v[12:13], v[12:13], v[234:235]
	global_store_dwordx4 v241, v[14:17], s[10:11] nt
	global_store_dwordx4 v241, v[10:13], s[10:11] offset:16 nt
	v_mul_f32_e32 v6, v6, v151
	v_mul_f32_e32 v7, v7, v151
	v_mul_f32_e32 v8, v8, v151
	v_mul_f32_e32 v9, v9, v151
	v_mul_f32_e32 v2, v2, v151
	v_mul_f32_e32 v3, v3, v151
	v_mul_f32_e32 v4, v4, v151
	v_mul_f32_e32 v5, v5, v151
	v_pk_mul_f32 v[6:7], v[6:7], v[236:237]
	v_pk_mul_f32 v[8:9], v[8:9], v[238:239]
	v_pk_mul_f32 v[2:3], v[2:3], v[140:141]
	v_pk_mul_f32 v[4:5], v[4:5], v[142:143]
	global_store_dwordx4 v241, v[6:9], s[10:11] offset:512 nt
	global_store_dwordx4 v241, v[2:5], s[10:11] offset:528 nt
